# slot rebalance: phase-1 slot W1B/WIN/WG (2496 tiles), phase-10 slot W2B + next-layer W1A/WBR/WO/WKV (3008 tiles), phase 0 keeps W2A + small
# speedup vs baseline: 1.0057x; 1.0057x over previous
; #define PH_BEGIN const int zi = opaque0(); unsigned char* ws = P.ws + zi; float* const OUT = P.out + zi; (void)OUT; const int tid = opqv((int)threadIdx.x); const int bid = opqs((int)blockIdx.x); const int G = opqs((int)gridDim.x); (void)tid; (void)bid; (void)G; unsigned char* WB = ws + WS_WB; float* SS = (float*)(ws + WS_SS); (void)WB; (void)SS; (void)zi;
; __global__ void __launch_bounds__(512) mega(Params P) {
;     ...
;         for (int rep = 0; rep < REPG; ++rep) {
;         { PH_BEGIN
;             pg8::Gemm g{XB_, (const bf16_t*)(WB + WB_W1A), T, 2 * FF, D, D, D, 0, 0}; pg8::StaticOrder S; S.init(T, 2 * FF, G, bid, 1);
;             EpiFFNa E{(bf16_t*)U_, SS + (size_t)0 * T * 16}; pg8::gemm_phase(lds, g, S, E, tid);
;         }
;         if ((int)blockIdx.x >= (int)gridDim.x - 16) { PH_BEGIN
;             pg8::Gemm g2{(const bf16_t*)(ws + WS_MEMN), (const bf16_t*)(WB + WB_WKV), 1024, D, D, D, D, 0, 0}; pg8::StaticOrder S2; S2.init(1024, D, 16, bid - (G - 16), 1);
;             EpiKV E2{KB_, VT_, (const float*)(ws + WS_MISC)}; pg8::gemm_phase(lds, g2, S2, E2, tid);
;         }
;         }
.LBB0_681:
	s_cmpk_lt_u32 s2, 0x80
	s_cbranch_scc1 .Lp1_noextra
	s_cmpk_gt_u32 s2, 0xef
	s_cbranch_scc1 .Lp1_noextra
	s_mul_i32 s1, s0, 0xab
	s_bfe_u32 s1, s1, 0x5000b
	s_and_b32 s16, s1, 0xffff
	s_lshl_b32 s19, s16, 10
	s_mov_b32 s28, 0xc000
	s_mov_b32 s29, 0xe000
	s_mov_b32 s72, 0xd000
	s_mov_b32 s73, 0x9000
	s_movk_i32 s74, 0x7000
	s_sub_i32 s2, s2, 0x80
	s_movk_i32 s3, 0x70
	s_mov_b32 s100, 1
	s_movk_i32 s101, 0x70
	s_branch .Lp0_mov_entry

; #define PH_BEGIN const int zi = opaque0(); unsigned char* ws = P.ws + zi; float* const OUT = P.out + zi; (void)OUT; const int tid = opqv((int)threadIdx.x); const int bid = opqs((int)blockIdx.x); const int G = opqs((int)gridDim.x); (void)tid; (void)bid; (void)G; unsigned char* WB = ws + WS_WB; float* SS = (float*)(ws + WS_SS); (void)WB; (void)SS; (void)zi;
; __global__ void __launch_bounds__(512) mega(Params P) {
;     ...
;             { PH_BEGIN convT_w<1>(INP(3) + (size_t)l * D * 2 * FF, 2 * FF, 0, INP(2) + (size_t)l * D, (bf16_t*)(WB + WB_W1A), D, D, 2 * FF, bid * 8 + (tid >> 6), G * 8, tid & 63, 0); }
.LBB0_682:
	s_and_b64 vcc, exec, s[4:5]
	s_cbranch_vccz .LBB0_778
	s_cmp_lg_u32 s96, 0
	s_cbranch_scc1 .LBB0_778
	s_mov_b32 s100, 0
	s_movk_i32 s101, 0x100
	s_cmp_eq_u32 s1, 0
	s_cbranch_scc1 .Lp10_w1a_entry
	s_or_b32 s2, s2, 0x10000
	s_mov_b32 s3, 0x100000

; #define PH_BEGIN const int zi = opaque0(); unsigned char* ws = P.ws + zi; float* const OUT = P.out + zi; (void)OUT; const int tid = opqv((int)threadIdx.x); const int bid = opqs((int)blockIdx.x); const int G = opqs((int)gridDim.x); (void)tid; (void)bid; (void)G; unsigned char* WB = ws + WS_WB; float* SS = (float*)(ws + WS_SS); (void)WB; (void)SS; (void)zi;
; __global__ void __launch_bounds__(512) mega(Params P) {
;     ...
;             { PH_BEGIN convT_w<0>(INP(7) + (size_t)l * D * 6928, 6928, 3856, INP(5) + (size_t)l * D, (bf16_t*)(WB + WB_WG), D, D, 3072, bid * 8 + (tid >> 6), G * 8, tid & 63, 3136); }
;             for (int j = 0; j < 3; ++j) { PH_BEGIN convT_w<0>(INP(27) + ((size_t)l * 3 + j) * 512 * D, D, 0, nullptr, (bf16_t*)(WB + WB_WBR) + (size_t)j * D * 512, 512, 512, D, bid * 8 + (tid >> 6), G * 8, tid & 63, 3904 + 128 * j); }
.LBB0_708:
	s_or_b64 exec, exec, s[4:5]
	s_cmp_eq_u32 s100, 1
	s_cbranch_scc1 .Lp1_back
	s_cmp_eq_u32 s100, 3
	s_cbranch_scc1 .Lh708_off
	s_cmp_eq_u32 s16, 0
	s_cbranch_scc0 .Lh708_done

; #define PH_BEGIN const int zi = opaque0(); unsigned char* ws = P.ws + zi; float* const OUT = P.out + zi; (void)OUT; const int tid = opqv((int)threadIdx.x); const int bid = opqs((int)blockIdx.x); const int G = opqs((int)gridDim.x); (void)tid; (void)bid; (void)G; unsigned char* WB = ws + WS_WB; float* SS = (float*)(ws + WS_SS); (void)WB; (void)SS; (void)zi;
; __global__ void __launch_bounds__(512) mega(Params P) {
;     ...
;             for (int j = 0; j < 3; ++j) { PH_BEGIN convT_w<0>(INP(27) + ((size_t)l * 3 + j) * 512 * D, D, 0, nullptr, (bf16_t*)(WB + WB_WBR) + (size_t)j * D * 512, 512, 512, D, bid * 8 + (tid >> 6), G * 8, tid & 63, 3904 + 128 * j); }
.Lh708_done:
	s_mov_b32 s62, 0
	s_branch .LBB0_710

; #define PH_BEGIN const int zi = opaque0(); unsigned char* ws = P.ws + zi; float* const OUT = P.out + zi; (void)OUT; const int tid = opqv((int)threadIdx.x); const int bid = opqs((int)blockIdx.x); const int G = opqs((int)gridDim.x); (void)tid; (void)bid; (void)G; unsigned char* WB = ws + WS_WB; float* SS = (float*)(ws + WS_SS); (void)WB; (void)SS; (void)zi;
; template <int MAP>
; __device__ __forceinline__ void convT_w(const float* src, int ld, int coff, const float* g, bf16_t* dst, int K, int Kd, int Nd, int wslot, int nslots, int lane, int tile_base) {
;     const int nkt = K >> 4, nnt = (Nd + 255) >> 8, ntile = nkt * nnt;
;     for (int t = ((wslot - tile_base) % nslots + nslots) % nslots; t < ntile; t += nslots) {
;         const int kt = t % nkt, ntl = t / nkt, k0 = kt * 16, n = ntl * 256 + lane * 4; const int c = (n < Nd) ? colmap<MAP>(n) : -1;
;         const float* sp = src + (size_t)k0 * ld + coff + (c >= 0 ? c : 0);
; __global__ void __launch_bounds__(512) mega(Params P) {
;     ...
;             { PH_BEGIN convT_w<1>(INP(30) + (size_t)l * D * 2 * FF, 2 * FF, 0, INP(29) + (size_t)l * D, (bf16_t*)(WB + WB_W2A), D, D, 2 * FF, bid * 8 + (tid >> 6), G * 8, tid & 63, 4800); }
.LBB0_727:
	s_or_b64 exec, exec, s[4:5]
	s_cmp_eq_u32 s100, 3
	s_cbranch_scc1 .Lp10_tramp_b
	s_and_b32 s2, s2, 0xffff
	s_mov_b32 s3, s101
	s_mov_b32 s4, s63
	v_mov_b32_e32 v0, v232
	s_mov_b32 s5, s2
	s_mov_b32 s6, s3
	s_lshl_b32 s20, s6, 3
	s_abs_i32 s6, s20
	s_waitcnt vmcnt(0)
	v_cvt_f32_u32_e32 v2, s6
	v_ashrrev_i32_e32 v3, 6, v0
	v_lshl_add_u32 v3, s5, 3, v3
	v_add_u32_e32 v3, 0xffffed40, v3
	v_rcp_iflag_f32_e32 v2, v2
	v_sub_u32_e32 v5, 0, v3
	s_sub_i32 s5, 0, s6
	v_ashrrev_i32_e32 v4, 31, v3
	v_mul_f32_e32 v2, 0x4f7ffffe, v2
	v_cvt_u32_f32_e32 v2, v2
	v_max_i32_e32 v3, v3, v5
	v_mul_lo_u32 v5, s5, v2
	v_mul_hi_u32 v5, v2, v5
	v_add_u32_e32 v2, v2, v5
	v_mul_hi_u32 v5, v3, v2
	v_mul_lo_u32 v5, v5, s6
	v_sub_u32_e32 v3, v3, v5
	v_subrev_u32_e32 v5, s6, v3
	v_cmp_le_u32_e32 vcc, s6, v3
	s_movk_i32 s5, 0x580
	s_nop 0
	v_cndmask_b32_e32 v3, v3, v5, vcc
	v_subrev_u32_e32 v5, s6, v3
	v_cmp_le_u32_e32 vcc, s6, v3
	s_nop 1
	v_cndmask_b32_e32 v3, v3, v5, vcc
	v_xor_b32_e32 v3, v3, v4
	v_sub_u32_e32 v3, v3, v4
	v_add_u32_e32 v3, s20, v3
	v_sub_u32_e32 v5, 0, v3
	v_ashrrev_i32_e32 v4, 31, v3
	v_max_i32_e32 v3, v3, v5
	v_mul_hi_u32 v2, v3, v2
	v_mul_lo_u32 v2, v2, s6
	v_sub_u32_e32 v2, v3, v2
	v_subrev_u32_e32 v3, s6, v2
	v_cmp_le_u32_e32 vcc, s6, v2
	s_nop 1
	v_cndmask_b32_e32 v2, v2, v3, vcc
	v_subrev_u32_e32 v3, s6, v2
	v_cmp_le_u32_e32 vcc, s6, v2
	s_nop 1
	v_cndmask_b32_e32 v2, v2, v3, vcc
	v_xor_b32_e32 v2, v2, v4
	v_sub_u32_e32 v20, v2, v4
	v_cmp_gt_i32_e32 vcc, s5, v20
	s_and_saveexec_b64 s[6:7], vcc
	s_cbranch_execz .LBB0_733
	v_readlane_b32 s36, v253, 39
	s_lshl_b32 s5, s17, 2
	v_readlane_b32 s48, v253, 51
	v_readlane_b32 s49, v253, 52
	s_add_u32 s8, s48, s5
	v_readlane_b32 s46, v253, 49
	s_addc_u32 s9, s49, 0
	v_readlane_b32 s47, v253, 50
	s_add_u32 s10, s46, s19
	s_addc_u32 s11, s47, 0
	s_ashr_i32 s5, s4, 31
	s_add_u32 s12, s92, s4
	s_addc_u32 s13, s93, s5
	s_lshl_b64 s[4:5], s[4:5], 2
	s_add_u32 s8, s8, s4
	s_addc_u32 s9, s9, s5
	s_add_u32 s10, s10, s4
	s_addc_u32 s11, s11, s5
	v_and_b32_e32 v0, 63, v0
	s_add_u32 s12, s12, 0x2980000
	v_lshlrev_b32_e32 v21, 2, v0
	s_addc_u32 s13, s13, 0
	v_cmp_gt_u32_e64 s[4:5], 32, v0
	v_add_u32_e32 v22, 0xa80, v21
	v_lshlrev_b32_e32 v23, 4, v20
	s_lshl_b32 s17, s20, 4
	s_mov_b64 s[14:15], 0
	v_readlane_b32 s37, v253, 40
	v_readlane_b32 s38, v253, 41
	v_readlane_b32 s39, v253, 42
	v_readlane_b32 s40, v253, 43
	v_readlane_b32 s41, v253, 44
	v_readlane_b32 s42, v253, 45
	v_readlane_b32 s43, v253, 46
	v_readlane_b32 s44, v253, 47
	v_readlane_b32 s45, v253, 48
	v_readlane_b32 s50, v253, 53
	v_readlane_b32 s51, v253, 54
	s_branch .LBB0_731
